# MLA attention: hand-scheduled fast path for unmasked half tiles (20 back-to-back MFMAs with 5-deep LDS prefetch, permlane32 swap instead of bpermute, O-rescale skipped when no row max grew)
# speedup vs baseline: 1.0487x; 1.0487x over previous
.LBB0_763:
	s_and_b32 s4, s77, 1
	s_add_i32 s5, s77, s4
	s_sub_i32 s4, 0, s4
	s_xor_b32 s4, s2, s4
	s_mul_i32 s5, s5, s30
	s_add_i32 s4, s5, s4
	s_cmpk_gt_i32 s4, 0x1ff
	s_cbranch_scc1 .LBB0_762
	s_and_b32 s86, s4, 7
	s_mul_i32 s5, s86, 0x180
	s_add_u32 s10, s40, s5
	s_addc_u32 s11, s60, 0
	s_mul_i32 s5, s86, 0x600000
	s_add_u32 s6, s61, s5
	s_addc_u32 s7, s72, 0
	s_lshl_b32 s5, s86, 22
	s_add_u32 s8, s73, s5
	v_mov_b32_e32 v22, v162
	s_addc_u32 s9, s74, 0
	s_lshl_b32 s4, s4, 5
	s_and_b32 s54, s4, 0xffffff00
	v_ashrrev_i32_e32 v0, 1, v22
	v_and_b32_e32 v0, 0xffffffe0, v0
	v_subrev_u32_e32 v38, s54, v0
	v_and_b32_e32 v36, 31, v22
	v_add_u32_e32 v186, 0x3f00, v38
	v_bfe_u32 v37, v22, 5, 1
	v_or_b32_e32 v158, v186, v36
	v_readfirstlane_b32 s12, v186
	s_mov_b32 s15, 0
	s_mov_b32 s19, 0
	s_nop 3
	s_bitcmp0_b32 s12, 7
	s_cselect_b32 s14, 1, 0
	v_mov_b64_e32 v[2:3], s[10:11]
	v_mad_i64_i32 v[2:3], s[4:5], v158, s45, v[2:3]
	v_lshlrev_b32_e32 v0, 4, v37
	v_lshl_add_u64 v[2:3], v[2:3], 0, v[0:1]
	global_load_dwordx4 v[82:85], v[2:3], off
	global_load_dwordx4 v[86:89], v[2:3], off offset:32
	global_load_dwordx4 v[90:93], v[2:3], off offset:64
	global_load_dwordx4 v[94:97], v[2:3], off offset:96
	global_load_dwordx4 v[98:101], v[2:3], off offset:128
	global_load_dwordx4 v[102:105], v[2:3], off offset:160
	global_load_dwordx4 v[106:109], v[2:3], off offset:192
	global_load_dwordx4 v[110:113], v[2:3], off offset:224
	global_load_dwordx4 v[114:117], v[2:3], off offset:256
	global_load_dwordx4 v[118:121], v[2:3], off offset:288
	global_load_dwordx4 v[122:125], v[2:3], off offset:320
	global_load_dwordx4 v[126:129], v[2:3], off offset:352
	v_add_u32_e32 v24, 0x200, v22
	v_ashrrev_i32_e32 v25, 31, v24
	v_ashrrev_i32_e32 v23, 31, v22
	v_lshrrev_b32_e32 v18, 29, v25
	v_lshrrev_b32_e32 v12, 29, v23
	v_add_u32_e32 v20, v24, v18
	v_add_u32_e32 v14, v22, v12
	v_ashrrev_i32_e32 v32, 3, v20
	v_and_b32_e32 v20, -8, v20
	v_lshlrev_b64 v[166:167], 4, v[24:25]
	v_add_u32_e32 v26, 0x400, v22
	v_ashrrev_i32_e32 v28, 3, v14
	v_and_b32_e32 v14, -8, v14
	v_ashrrev_i32_e32 v33, 31, v32
	v_sub_u32_e32 v25, v24, v20
	v_lshlrev_b64 v[160:161], 4, v[22:23]
	v_ashrrev_i32_e32 v27, 31, v26
	v_ashrrev_i32_e32 v29, 31, v28
	v_sub_u32_e32 v23, v22, v14
	v_lshlrev_b64 v[174:175], 15, v[32:33]
	v_lshlrev_b32_e32 v176, 3, v25
	v_lshlrev_b64 v[168:169], 4, v[26:27]
	v_lshlrev_b64 v[170:171], 15, v[28:29]
	v_lshlrev_b32_e32 v172, 3, v23
	v_lshl_add_u64 v[18:19], s[8:9], 0, v[174:175]
	v_ashrrev_i32_e32 v177, 31, v176
	v_lshl_add_u64 v[2:3], s[6:7], 0, v[160:161]
	v_lshl_add_u64 v[6:7], s[6:7], 0, v[166:167]
	v_lshl_add_u64 v[10:11], s[6:7], 0, v[168:169]
	v_lshl_add_u64 v[12:13], s[8:9], 0, v[170:171]
	v_ashrrev_i32_e32 v173, 31, v172
	v_lshl_add_u64 v[34:35], v[176:177], 1, v[18:19]
	global_load_dwordx4 v[2:5], v[2:3], off
	s_nop 0
	global_load_dwordx4 v[6:9], v[6:7], off
	v_lshl_add_u64 v[30:31], v[172:173], 1, v[12:13]
	global_load_dwordx4 v[10:13], v[10:11], off
	s_nop 0
	global_load_dwordx4 v[14:17], v[30:31], off
	global_load_dwordx4 v[18:21], v[34:35], off
	s_sub_i32 s4, 0x4000, s54
	v_and_b32_e32 v27, 63, v22
	v_ashrrev_i32_e32 v159, 31, v158
	v_mul_hi_i32 v29, v22, s29
	v_lshrrev_b32_e32 v33, 31, v29
	v_ashrrev_i32_e32 v29, 2, v29
	v_add_u32_e32 v29, v29, v33
	v_mul_lo_u32 v187, v29, s48
	v_mul_lo_u32 v29, v29, 24
	v_sub_u32_e32 v22, v22, v29
	v_lshlrev_b32_e32 v188, 4, v22
	v_add3_u32 v22, s78, v187, v188
	s_waitcnt vmcnt(4)
	ds_write_b128 v22, v[2:5]
	v_mul_hi_i32 v2, v24, s29
	v_lshrrev_b32_e32 v3, 31, v2
	v_ashrrev_i32_e32 v2, 2, v2
	v_add_u32_e32 v2, v2, v3
	v_mul_lo_u32 v189, v2, s48
	v_mul_lo_u32 v2, v2, 24
	v_sub_u32_e32 v2, v24, v2
	v_lshlrev_b32_e32 v190, 4, v2
	v_add3_u32 v2, s78, v189, v190
	s_waitcnt vmcnt(3)
	ds_write_b128 v2, v[6:9]
	v_mul_hi_i32 v2, v26, s29
	v_lshrrev_b32_e32 v3, 31, v2
	v_ashrrev_i32_e32 v2, 2, v2
	v_add_u32_e32 v2, v2, v3
	v_mul_lo_u32 v191, v2, s48
	v_mul_lo_u32 v2, v2, 24
	v_sub_u32_e32 v2, v26, v2
	v_lshlrev_b32_e32 v192, 4, v2
	s_movk_i32 s5, 0x90
	v_add3_u32 v2, s78, v191, v192
	v_mul_lo_u32 v193, v28, s5
	v_lshlrev_b32_e32 v194, 4, v23
	s_waitcnt vmcnt(2)
	ds_write_b128 v2, v[10:13]
	v_add3_u32 v2, s78, v193, v194
	v_mul_lo_u32 v195, v32, s5
	v_lshlrev_b32_e32 v196, 4, v25
	s_add_u32 s10, s6, 0x6000
	s_waitcnt vmcnt(1)
	ds_write_b128 v2, v[14:17] offset:51200
	v_add3_u32 v2, s78, v195, v196
	s_addc_u32 s11, s7, 0
	s_waitcnt vmcnt(0)
	ds_write_b128 v2, v[18:21] offset:51200
	v_lshl_add_u64 v[2:3], s[10:11], 0, v[160:161]
	global_load_dwordx4 v[130:133], v[2:3], off
	v_lshl_add_u64 v[2:3], s[10:11], 0, v[166:167]
	global_load_dwordx4 v[134:137], v[2:3], off
	v_lshl_add_u64 v[2:3], s[10:11], 0, v[168:169]
	global_load_dwordx4 v[138:141], v[2:3], off
	global_load_dwordx4 v[142:145], v[30:31], off offset:128
	global_load_dwordx4 v[146:149], v[34:35], off offset:128
	s_movk_i32 s49, 0x90
	s_lshr_b32 s87, s4, 6
	v_mul_u32_u24_e32 v2, 0x190, v36
	v_add3_u32 v202, s78, v2, v0
	v_lshlrev_b32_e32 v2, 2, v27
	v_mov_b32_e32 v50, v1
	v_mov_b32_e32 v51, v1
	v_add_u32_e32 v201, 0x3f3f, v38
	v_add_u32_e32 v203, 0x3f1f, v38
	v_lshlrev_b32_e32 v197, 2, v37
	v_xor_b32_e32 v198, 0x80, v2
	v_mul_u32_u24_e32 v200, 0x90, v36
	v_mov_b32_e32 v52, v1
	v_mov_b32_e32 v53, v1
	v_mov_b32_e32 v54, v1
	v_mov_b32_e32 v55, v1
	v_mov_b32_e32 v56, v1
	v_mov_b32_e32 v57, v1
	v_mov_b32_e32 v58, v1
	v_mov_b32_e32 v59, v1
	v_mov_b32_e32 v60, v1
	v_mov_b32_e32 v61, v1
	v_mov_b32_e32 v62, v1
	v_mov_b32_e32 v63, v1
	v_mov_b32_e32 v64, v1
	v_mov_b32_e32 v65, v1
	v_readlane_b32 s5, v246, 59
	v_mov_b64_e32 v[34:35], v[50:51]
	v_mov_b64_e32 v[18:19], v[50:51]
	v_mov_b64_e32 v[2:3], v[50:51]
	s_mov_b32 s4, 0
	v_mov_b32_e32 v199, 0
	v_mov_b32_e32 v206, 0xf149f2ca
	v_mov_b32_e32 v209, s5
	v_mov_b32_e32 v154, 0
	v_mov_b32_e32 v155, 0
	v_mov_b32_e32 v156, 0
	v_mov_b32_e32 v157, 0
	v_mov_b32_e32 v150, 0
	v_mov_b32_e32 v151, 0
	v_mov_b32_e32 v152, 0
	v_mov_b32_e32 v153, 0
	v_mov_b64_e32 v[36:37], v[52:53]
	v_mov_b64_e32 v[38:39], v[54:55]
	v_mov_b64_e32 v[40:41], v[56:57]
	v_mov_b64_e32 v[42:43], v[58:59]
	v_mov_b64_e32 v[44:45], v[60:61]
	v_mov_b64_e32 v[46:47], v[62:63]
	v_mov_b64_e32 v[48:49], v[64:65]
	v_mov_b64_e32 v[20:21], v[52:53]
	v_mov_b64_e32 v[22:23], v[54:55]
	v_mov_b64_e32 v[24:25], v[56:57]
	v_mov_b64_e32 v[26:27], v[58:59]
	v_mov_b64_e32 v[28:29], v[60:61]
	v_mov_b64_e32 v[30:31], v[62:63]
	v_mov_b64_e32 v[32:33], v[64:65]
	v_mov_b64_e32 v[4:5], v[52:53]
	v_mov_b64_e32 v[6:7], v[54:55]
	v_mov_b64_e32 v[8:9], v[56:57]
	v_mov_b64_e32 v[10:11], v[58:59]
	v_mov_b64_e32 v[12:13], v[60:61]
	v_mov_b64_e32 v[14:15], v[62:63]
	v_mov_b64_e32 v[16:17], v[64:65]
	s_waitcnt lgkmcnt(0)
	s_barrier
	s_and_b32 s5, s4, 1
	s_add_i32 s88, s4, 1
	s_cmp_ge_u32 s88, s87
	s_cbranch_scc1 .LBB0_766

.Lmla_tail:
	s_xor_b64 s[4:5], s[10:11], -1
	s_mov_b32 s90, 1
	s_mov_b64 s[10:11], 0
	s_and_b64 vcc, exec, s[4:5]
	s_cbranch_vccnz .LBB0_776
.LBB0_772:
	s_lshl_b32 s4, s90, 5
	s_or_b32 s91, s4, s54
	s_add_i32 s13, s91, 31
	s_cmp_le_i32 s13, s12
	s_cbranch_scc1 .Lmla_fast
	v_cmp_le_i32_e32 vcc, s91, v201
	s_and_saveexec_b64 s[82:83], vcc
	s_cbranch_execz .LBB0_771
	s_or_b32 s4, s91, 31
	v_subrev_u32_e32 v66, s4, v186
	v_cmp_gt_i32_e32 vcc, 2.0, v66
	s_and_saveexec_b64 s[84:85], vcc
	s_cbranch_execz .LBB0_770
	s_mul_i32 s5, s90, 0x3200
	v_add_u32_e32 v205, s5, v204
	ds_read_b128 v[66:69], v205
	ds_read_b128 v[210:213], v205 offset:32
	ds_read_b128 v[214:217], v205 offset:64
	s_waitcnt lgkmcnt(2)
	v_mfma_f32_32x32x16_bf16 v[66:81], v[66:69], v[82:85], 0
	ds_read_b128 v[218:221], v205 offset:96
	s_waitcnt lgkmcnt(2)
	v_mfma_f32_32x32x16_bf16 v[66:81], v[210:213], v[86:89], v[66:81]
	ds_read_b128 v[210:213], v205 offset:128
	s_waitcnt lgkmcnt(2)
	v_mfma_f32_32x32x16_bf16 v[66:81], v[214:217], v[90:93], v[66:81]
	ds_read_b128 v[214:217], v205 offset:160
	s_waitcnt lgkmcnt(2)
	v_mfma_f32_32x32x16_bf16 v[66:81], v[218:221], v[94:97], v[66:81]
	ds_read_b128 v[218:221], v205 offset:192
	s_waitcnt lgkmcnt(2)
	v_mfma_f32_32x32x16_bf16 v[66:81], v[210:213], v[98:101], v[66:81]
	ds_read_b128 v[210:213], v205 offset:224
	s_waitcnt lgkmcnt(2)
	v_mfma_f32_32x32x16_bf16 v[66:81], v[214:217], v[102:105], v[66:81]
	ds_read_b128 v[214:217], v205 offset:256
	s_waitcnt lgkmcnt(2)
	v_mfma_f32_32x32x16_bf16 v[66:81], v[218:221], v[106:109], v[66:81]
	ds_read_b128 v[218:221], v205 offset:288
	s_waitcnt lgkmcnt(2)
	v_mfma_f32_32x32x16_bf16 v[66:81], v[210:213], v[110:113], v[66:81]
	ds_read_b128 v[210:213], v205 offset:320
	s_waitcnt lgkmcnt(2)
	v_mfma_f32_32x32x16_bf16 v[66:81], v[214:217], v[114:117], v[66:81]
	ds_read_b128 v[214:217], v205 offset:352
	s_waitcnt lgkmcnt(2)
	v_mfma_f32_32x32x16_bf16 v[66:81], v[218:221], v[118:121], v[66:81]
	s_waitcnt lgkmcnt(1)
	v_mfma_f32_32x32x16_bf16 v[66:81], v[210:213], v[122:125], v[66:81]
	s_waitcnt lgkmcnt(0)
	v_mfma_f32_32x32x16_bf16 v[66:81], v[214:217], v[126:129], v[66:81]
	v_cmp_gt_i32_e32 vcc, s4, v186
	v_subrev_u32_e32 v205, s91, v203
	s_brev_b32 s4, -4
	v_cmp_lt_i32_e64 s[4:5], s4, v205
	s_or_b64 s[4:5], vcc, s[4:5]
	s_and_saveexec_b64 s[58:59], s[4:5]
	s_cbranch_execz .LBB0_769
	v_or_b32_e32 v205, s91, v197
	v_sub_u32_e32 v207, v158, v205
	v_cmp_le_i32_e32 vcc, v205, v158
	v_cmp_gt_i32_e64 s[4:5], 2.0, v207
	s_and_b64 vcc, vcc, s[4:5]
	v_sub_u32_e32 v207, v205, v158
	s_brev_b32 s4, -3
	v_cndmask_b32_e32 v66, v184, v66, vcc
	v_cmp_lt_i32_e32 vcc, v205, v158
	v_cmp_lt_i32_e64 s[4:5], s4, v207
	s_and_b64 vcc, vcc, s[4:5]
	v_or_b32_e32 v207, 2, v205
	v_cndmask_b32_e32 v67, v184, v67, vcc
	v_cmp_ge_i32_e32 vcc, v158, v207
	v_sub_u32_e32 v207, v158, v207
	v_cmp_gt_i32_e64 s[4:5], 2.0, v207
	s_and_b64 vcc, vcc, s[4:5]
	v_or_b32_e32 v207, 3, v205
	v_cndmask_b32_e32 v68, v184, v68, vcc
	v_cmp_ge_i32_e32 vcc, v158, v207
	v_sub_u32_e32 v207, v158, v207
	v_cmp_gt_i32_e64 s[4:5], 2.0, v207
	s_and_b64 vcc, vcc, s[4:5]
	v_or_b32_e32 v207, 8, v205
	v_cndmask_b32_e32 v69, v184, v69, vcc
	v_cmp_ge_i32_e32 vcc, v158, v207
	v_sub_u32_e32 v207, v158, v207
	v_cmp_gt_i32_e64 s[4:5], 2.0, v207
	s_and_b64 vcc, vcc, s[4:5]
	v_or_b32_e32 v207, 9, v205
	v_cndmask_b32_e32 v70, v184, v70, vcc
	v_cmp_ge_i32_e32 vcc, v158, v207
	v_sub_u32_e32 v207, v158, v207
	v_cmp_gt_i32_e64 s[4:5], 2.0, v207
	s_and_b64 vcc, vcc, s[4:5]
	v_or_b32_e32 v207, 10, v205
	v_cndmask_b32_e32 v71, v184, v71, vcc
	v_cmp_ge_i32_e32 vcc, v158, v207
	v_sub_u32_e32 v207, v158, v207
	v_cmp_gt_i32_e64 s[4:5], 2.0, v207
	s_and_b64 vcc, vcc, s[4:5]
	v_or_b32_e32 v207, 11, v205
	v_cndmask_b32_e32 v72, v184, v72, vcc
	v_cmp_ge_i32_e32 vcc, v158, v207
	v_sub_u32_e32 v207, v158, v207
	v_cmp_gt_i32_e64 s[4:5], 2.0, v207
	s_and_b64 vcc, vcc, s[4:5]
	v_or_b32_e32 v207, 16, v205
	v_cndmask_b32_e32 v73, v184, v73, vcc
	v_cmp_ge_i32_e32 vcc, v158, v207
	v_sub_u32_e32 v207, v158, v207
	v_cmp_gt_i32_e64 s[4:5], 2.0, v207
	s_and_b64 vcc, vcc, s[4:5]
	v_or_b32_e32 v207, 17, v205
	v_cndmask_b32_e32 v74, v184, v74, vcc
	v_cmp_ge_i32_e32 vcc, v158, v207
	v_sub_u32_e32 v207, v158, v207
	v_cmp_gt_i32_e64 s[4:5], 2.0, v207
	s_and_b64 vcc, vcc, s[4:5]
	v_or_b32_e32 v207, 18, v205
	v_cndmask_b32_e32 v75, v184, v75, vcc
	v_cmp_ge_i32_e32 vcc, v158, v207
	v_sub_u32_e32 v207, v158, v207
	v_cmp_gt_i32_e64 s[4:5], 2.0, v207
	s_and_b64 vcc, vcc, s[4:5]
	v_or_b32_e32 v207, 19, v205
	v_cndmask_b32_e32 v76, v184, v76, vcc
	v_cmp_ge_i32_e32 vcc, v158, v207
	v_sub_u32_e32 v207, v158, v207
	v_cmp_gt_i32_e64 s[4:5], 2.0, v207
	s_and_b64 vcc, vcc, s[4:5]
	v_or_b32_e32 v207, 24, v205
	v_cndmask_b32_e32 v77, v184, v77, vcc
	v_cmp_ge_i32_e32 vcc, v158, v207
	v_sub_u32_e32 v207, v158, v207
	v_cmp_gt_i32_e64 s[4:5], 2.0, v207
	s_and_b64 vcc, vcc, s[4:5]
	v_or_b32_e32 v207, 25, v205
	v_cndmask_b32_e32 v78, v184, v78, vcc
	v_cmp_ge_i32_e32 vcc, v158, v207
	v_sub_u32_e32 v207, v158, v207
	v_cmp_gt_i32_e64 s[4:5], 2.0, v207
	s_and_b64 vcc, vcc, s[4:5]
	v_or_b32_e32 v207, 26, v205
	v_cndmask_b32_e32 v79, v184, v79, vcc
	v_cmp_ge_i32_e32 vcc, v158, v207
	v_sub_u32_e32 v207, v158, v207
	v_cmp_gt_i32_e64 s[4:5], 2.0, v207
	s_and_b64 vcc, vcc, s[4:5]
	v_or_b32_e32 v205, 27, v205
	v_cndmask_b32_e32 v80, v184, v80, vcc
	v_cmp_ge_i32_e32 vcc, v158, v205
	v_sub_u32_e32 v205, v158, v205
	v_cmp_gt_i32_e64 s[4:5], 2.0, v205
	s_and_b64 vcc, vcc, s[4:5]
	v_cndmask_b32_e32 v81, v184, v81, vcc
	s_branch .LBB0_769
.Lmla_fast:
	s_mul_i32 s5, s90, 0x3200
	v_add_u32_e32 v205, s5, v204
	v_add3_u32 v234, v209, v0, v200
	ds_read_b128 v[210:213], v205
	ds_read_b128 v[214:217], v205 offset:32
	ds_read_b128 v[218:221], v205 offset:64
	ds_read_b128 v[222:225], v205 offset:96
	ds_read_b128 v[226:229], v205 offset:128
	s_lshl_b32 s4, s90, 6
	s_add_i32 s4, s89, s4
	s_add_i32 s4, s4, 0xc800
	v_mov_b32_e32 v209, s4
	s_waitcnt lgkmcnt(4)
	v_mfma_f32_32x32x16_bf16 v[66:81], v[210:213], v[82:85], 0
	ds_read_b128 v[230:233], v205 offset:160
	s_waitcnt lgkmcnt(4)
	v_mfma_f32_32x32x16_bf16 v[66:81], v[214:217], v[86:89], v[66:81]
	ds_read_b128 v[210:213], v205 offset:192
	s_waitcnt lgkmcnt(4)
	v_mfma_f32_32x32x16_bf16 v[66:81], v[218:221], v[90:93], v[66:81]
	ds_read_b128 v[214:217], v205 offset:224
	s_waitcnt lgkmcnt(4)
	v_mfma_f32_32x32x16_bf16 v[66:81], v[222:225], v[94:97], v[66:81]
	ds_read_b128 v[218:221], v205 offset:256
	s_waitcnt lgkmcnt(4)
	v_mfma_f32_32x32x16_bf16 v[66:81], v[226:229], v[98:101], v[66:81]
	ds_read_b128 v[222:225], v205 offset:288
	s_waitcnt lgkmcnt(4)
	v_mfma_f32_32x32x16_bf16 v[66:81], v[230:233], v[102:105], v[66:81]
	ds_read_b128 v[226:229], v205 offset:320
	s_waitcnt lgkmcnt(4)
	v_mfma_f32_32x32x16_bf16 v[66:81], v[210:213], v[106:109], v[66:81]
	ds_read_b128 v[230:233], v205 offset:352
	s_waitcnt lgkmcnt(4)
	v_mfma_f32_32x32x16_bf16 v[66:81], v[214:217], v[110:113], v[66:81]
	ds_read_b128 v[210:213], v234
	s_waitcnt lgkmcnt(4)
	v_mfma_f32_32x32x16_bf16 v[66:81], v[218:221], v[114:117], v[66:81]
	ds_read_b128 v[214:217], v234 offset:4608
	s_waitcnt lgkmcnt(4)
	v_mfma_f32_32x32x16_bf16 v[66:81], v[222:225], v[118:121], v[66:81]
	ds_read_b128 v[218:221], v234 offset:9216
	s_waitcnt lgkmcnt(4)
	v_mfma_f32_32x32x16_bf16 v[66:81], v[226:229], v[122:125], v[66:81]
	ds_read_b128 v[222:225], v234 offset:13824
	s_waitcnt lgkmcnt(4)
	v_mfma_f32_32x32x16_bf16 v[66:81], v[230:233], v[126:129], v[66:81]
	ds_read_b128 v[226:229], v234 offset:32
	s_waitcnt lgkmcnt(4)
	v_mfma_f32_32x32x16_bf16 v[50:65], v[210:213], v[154:157], v[50:65]
	ds_read_b128 v[230:233], v234 offset:4640
	s_waitcnt lgkmcnt(4)
	v_mfma_f32_32x32x16_bf16 v[34:49], v[214:217], v[154:157], v[34:49]
	ds_read_b128 v[210:213], v234 offset:9248
	s_waitcnt lgkmcnt(4)
	v_mfma_f32_32x32x16_bf16 v[18:33], v[218:221], v[154:157], v[18:33]
	ds_read_b128 v[214:217], v234 offset:13856
	s_waitcnt lgkmcnt(4)
	v_mfma_f32_32x32x16_bf16 v[2:17], v[222:225], v[154:157], v[2:17]
	s_waitcnt lgkmcnt(3)
	v_mfma_f32_32x32x16_bf16 v[50:65], v[226:229], v[150:153], v[50:65]
	s_waitcnt lgkmcnt(2)
	v_mfma_f32_32x32x16_bf16 v[34:49], v[230:233], v[150:153], v[34:49]
	s_waitcnt lgkmcnt(1)
	v_mfma_f32_32x32x16_bf16 v[18:33], v[210:213], v[150:153], v[18:33]
	s_waitcnt lgkmcnt(0)
	v_mfma_f32_32x32x16_bf16 v[2:17], v[214:217], v[150:153], v[2:17]
.Lmla_sm:
	v_max3_f32 v207, v66, v67, v68
	v_max3_f32 v208, v74, v75, v76
	v_max3_f32 v207, v207, v69, v70
	v_max3_f32 v208, v208, v77, v78
	v_max3_f32 v207, v207, v71, v72
	v_max3_f32 v208, v208, v79, v80
	v_max3_f32 v207, v207, v73, v81
	v_max_f32_e32 v207, v207, v208
	v_mov_b32_e32 v208, v207
	s_nop 1
	v_permlane32_swap_b32_e32 v207, v208
	v_max3_f32 v205, v206, v207, v208
	v_sub_f32_e32 v236, v206, v205
	v_cmp_lt_f32_e32 vcc, v206, v205
	v_sub_f32_e32 v66, v66, v205
	v_exp_f32_e32 v66, v66
	v_sub_f32_e32 v67, v67, v205
	v_exp_f32_e32 v67, v67
	v_add_f32_e32 v235, 0, v66
	v_sub_f32_e32 v68, v68, v205
	v_exp_f32_e32 v68, v68
	v_add_f32_e32 v235, v67, v235
	v_sub_f32_e32 v69, v69, v205
	v_exp_f32_e32 v69, v69
	v_add_f32_e32 v235, v68, v235
	v_sub_f32_e32 v70, v70, v205
	v_exp_f32_e32 v70, v70
	v_add_f32_e32 v235, v69, v235
	v_sub_f32_e32 v71, v71, v205
	v_exp_f32_e32 v71, v71
	v_add_f32_e32 v235, v70, v235
	v_sub_f32_e32 v72, v72, v205
	v_exp_f32_e32 v72, v72
	v_add_f32_e32 v235, v71, v235
	v_sub_f32_e32 v73, v73, v205
	v_exp_f32_e32 v73, v73
	v_add_f32_e32 v235, v72, v235
	v_sub_f32_e32 v74, v74, v205
	v_exp_f32_e32 v74, v74
	v_add_f32_e32 v235, v73, v235
	v_sub_f32_e32 v75, v75, v205
	v_exp_f32_e32 v75, v75
	v_add_f32_e32 v235, v74, v235
	v_sub_f32_e32 v76, v76, v205
	v_exp_f32_e32 v76, v76
	v_add_f32_e32 v235, v75, v235
	v_sub_f32_e32 v77, v77, v205
	v_exp_f32_e32 v77, v77
	v_add_f32_e32 v235, v76, v235
	v_sub_f32_e32 v78, v78, v205
	v_exp_f32_e32 v78, v78
	v_add_f32_e32 v235, v77, v235
	v_sub_f32_e32 v79, v79, v205
	v_exp_f32_e32 v79, v79
	v_add_f32_e32 v235, v78, v235
	v_sub_f32_e32 v80, v80, v205
	v_exp_f32_e32 v80, v80
	v_add_f32_e32 v235, v79, v235
	v_sub_f32_e32 v81, v81, v205
	v_exp_f32_e32 v81, v81
	v_add_f32_e32 v235, v80, v235
	v_exp_f32_e32 v236, v236
	v_add_f32_e32 v235, v81, v235
	s_nop 0
	v_fmac_f32_e32 v235, v199, v236
	s_cbranch_vccz .Lmla_norescale
	v_pk_mul_f32 v[64:65], v[64:65], v[236:237] op_sel_hi:[1,0]
	v_pk_mul_f32 v[62:63], v[62:63], v[236:237] op_sel_hi:[1,0]
	v_pk_mul_f32 v[60:61], v[60:61], v[236:237] op_sel_hi:[1,0]
	v_pk_mul_f32 v[58:59], v[58:59], v[236:237] op_sel_hi:[1,0]
	v_pk_mul_f32 v[56:57], v[56:57], v[236:237] op_sel_hi:[1,0]
	v_pk_mul_f32 v[54:55], v[54:55], v[236:237] op_sel_hi:[1,0]
	v_pk_mul_f32 v[52:53], v[52:53], v[236:237] op_sel_hi:[1,0]
	v_pk_mul_f32 v[50:51], v[50:51], v[236:237] op_sel_hi:[1,0]
	v_pk_mul_f32 v[48:49], v[48:49], v[236:237] op_sel_hi:[1,0]
	v_pk_mul_f32 v[46:47], v[46:47], v[236:237] op_sel_hi:[1,0]
	v_pk_mul_f32 v[44:45], v[44:45], v[236:237] op_sel_hi:[1,0]
	v_pk_mul_f32 v[42:43], v[42:43], v[236:237] op_sel_hi:[1,0]
	v_pk_mul_f32 v[40:41], v[40:41], v[236:237] op_sel_hi:[1,0]
	v_pk_mul_f32 v[38:39], v[38:39], v[236:237] op_sel_hi:[1,0]
	v_pk_mul_f32 v[36:37], v[36:37], v[236:237] op_sel_hi:[1,0]
	v_pk_mul_f32 v[34:35], v[34:35], v[236:237] op_sel_hi:[1,0]
	v_pk_mul_f32 v[32:33], v[32:33], v[236:237] op_sel_hi:[1,0]
	v_pk_mul_f32 v[30:31], v[30:31], v[236:237] op_sel_hi:[1,0]
	v_pk_mul_f32 v[28:29], v[28:29], v[236:237] op_sel_hi:[1,0]
	v_pk_mul_f32 v[26:27], v[26:27], v[236:237] op_sel_hi:[1,0]
	v_pk_mul_f32 v[24:25], v[24:25], v[236:237] op_sel_hi:[1,0]
	v_pk_mul_f32 v[22:23], v[22:23], v[236:237] op_sel_hi:[1,0]
	v_pk_mul_f32 v[20:21], v[20:21], v[236:237] op_sel_hi:[1,0]
	v_pk_mul_f32 v[18:19], v[18:19], v[236:237] op_sel_hi:[1,0]
	v_pk_mul_f32 v[16:17], v[16:17], v[236:237] op_sel_hi:[1,0]
	v_pk_mul_f32 v[14:15], v[14:15], v[236:237] op_sel_hi:[1,0]
	v_pk_mul_f32 v[12:13], v[12:13], v[236:237] op_sel_hi:[1,0]
	v_pk_mul_f32 v[10:11], v[10:11], v[236:237] op_sel_hi:[1,0]
	v_pk_mul_f32 v[8:9], v[8:9], v[236:237] op_sel_hi:[1,0]
	v_pk_mul_f32 v[6:7], v[6:7], v[236:237] op_sel_hi:[1,0]
	v_pk_mul_f32 v[4:5], v[4:5], v[236:237] op_sel_hi:[1,0]
	v_pk_mul_f32 v[2:3], v[2:3], v[236:237] op_sel_hi:[1,0]
.Lmla_norescale:
	v_cvt_pk_bf16_f32 v154, v66, v67
	v_cvt_pk_bf16_f32 v155, v68, v69
	v_cvt_pk_bf16_f32 v156, v70, v71
	v_cvt_pk_bf16_f32 v157, v72, v73
	v_cvt_pk_bf16_f32 v150, v74, v75
	v_cvt_pk_bf16_f32 v151, v76, v77
	v_cvt_pk_bf16_f32 v152, v78, v79
	v_cvt_pk_bf16_f32 v153, v80, v81
	v_mov_b32_e32 v206, v205
	v_mov_b32_e32 v199, v235
	s_branch .Lmla_tail

	.amdhsa_kernel _Z14fwd_megakernel6Params
		.amdhsa_group_segment_fixed_size 1024
		.amdhsa_private_segment_fixed_size 0
		.amdhsa_kernarg_size 456
		.amdhsa_user_sgpr_count 2
		.amdhsa_user_sgpr_dispatch_ptr 0
		.amdhsa_user_sgpr_queue_ptr 0
		.amdhsa_user_sgpr_kernarg_segment_ptr 1
		.amdhsa_user_sgpr_dispatch_id 0
		.amdhsa_user_sgpr_kernarg_preload_length 0
		.amdhsa_user_sgpr_kernarg_preload_offset 0
		.amdhsa_user_sgpr_private_segment_size 0
		.amdhsa_uses_dynamic_stack 0
		.amdhsa_enable_private_segment 0
		.amdhsa_system_sgpr_workgroup_id_x 1
		.amdhsa_system_sgpr_workgroup_id_y 0
		.amdhsa_system_sgpr_workgroup_id_z 0
		.amdhsa_system_sgpr_workgroup_info 0
		.amdhsa_system_vgpr_workitem_id 2
		.amdhsa_next_free_vgpr 247
		.amdhsa_next_free_sgpr 102
		.amdhsa_accum_offset 248
		.amdhsa_reserve_vcc 1
		.amdhsa_float_round_mode_32 0
		.amdhsa_float_round_mode_16_64 0
		.amdhsa_float_denorm_mode_32 3
		.amdhsa_float_denorm_mode_16_64 3
		.amdhsa_dx10_clamp 1
		.amdhsa_ieee_mode 1
		.amdhsa_fp16_overflow 0
		.amdhsa_tg_split 0
		.amdhsa_exception_fp_ieee_invalid_op 0
		.amdhsa_exception_fp_denorm_src 0
		.amdhsa_exception_fp_ieee_div_zero 0
		.amdhsa_exception_fp_ieee_overflow 0
		.amdhsa_exception_fp_ieee_underflow 0
		.amdhsa_exception_fp_ieee_inexact 0
		.amdhsa_exception_int_div_zero 0
	.end_amdhsa_kernel

amdhsa.kernels:
  - .agpr_count:     0
    .args:
      - .offset:         0
        .size:           200
        .value_kind:     by_value
      - .offset:         200
        .size:           4
        .value_kind:     hidden_block_count_x
      - .offset:         204
        .size:           4
        .value_kind:     hidden_block_count_y
      - .offset:         208
        .size:           4
        .value_kind:     hidden_block_count_z
      - .offset:         212
        .size:           2
        .value_kind:     hidden_group_size_x
      - .offset:         214
        .size:           2
        .value_kind:     hidden_group_size_y
      - .offset:         216
        .size:           2
        .value_kind:     hidden_group_size_z
      - .offset:         218
        .size:           2
        .value_kind:     hidden_remainder_x
      - .offset:         220
        .size:           2
        .value_kind:     hidden_remainder_y
      - .offset:         222
        .size:           2
        .value_kind:     hidden_remainder_z
      - .offset:         240
        .size:           8
        .value_kind:     hidden_global_offset_x
      - .offset:         248
        .size:           8
        .value_kind:     hidden_global_offset_y
      - .offset:         256
        .size:           8
        .value_kind:     hidden_global_offset_z
      - .offset:         264
        .size:           2
        .value_kind:     hidden_grid_dims
      - .offset:         288
        .size:           8
        .value_kind:     hidden_multigrid_sync_arg
      - .offset:         320
        .size:           4
        .value_kind:     hidden_dynamic_lds_size
    .group_segment_fixed_size: 1024
    .kernarg_segment_align: 8
    .kernarg_segment_size: 456
    .language:       OpenCL C
    .language_version:
      - 2
      - 0
    .max_flat_workgroup_size: 512
    .name:           _Z14fwd_megakernel6Params
    .private_segment_fixed_size: 0
    .sgpr_count:     108
    .sgpr_spill_count: 60
    .symbol:         _Z14fwd_megakernel6Params.kd
    .uniform_work_group_size: 1
    .uses_dynamic_stack: false
    .vgpr_count:     247
    .vgpr_spill_count: 0
    .wavefront_size: 64
